# fin9 plus one static s_setprio 1 for the two conv-stage waves that also carry the per-row decay work (reset at the stage barrier)
# baseline (speedup 1.0000x reference)
.LBB0_598:
	s_or_b64 exec, exec, s[0:1]
	s_mov_b64 vcc, s[24:25]
	s_cmp_lg_u64 s[46:47], 0
	s_cbranch_scc0 .Lprio_skip
	s_setprio 1
.Lprio_skip:
	s_waitcnt vmcnt(14)
	v_lshlrev_b32_e32 v154, 16, v145
	v_and_b32_e32 v155, 0xffff0000, v145
	v_and_or_b32 v169, v0, 4, v150
	v_lshlrev_b32_e32 v150, 16, v133
	v_and_b32_e32 v151, 0xffff0000, v133
	s_waitcnt vmcnt(10)
	v_pk_mul_f32 v[152:153], v[124:125], v[154:155]
	v_lshlrev_b32_e32 v172, 16, v132
	v_pk_fma_f32 v[152:153], v[120:121], v[150:151], v[152:153]
	v_lshlrev_b32_e32 v150, 16, v141
	v_and_b32_e32 v151, 0xffff0000, v141
	s_waitcnt vmcnt(8)
	v_pk_fma_f32 v[152:153], v[128:129], v[150:151], v[152:153]
	v_and_b32_e32 v173, 0xffff0000, v132
	v_mul_f32_e32 v0, 0xbfb8aa3b, v152
	v_exp_f32_e32 v133, v0
	v_mul_f32_e32 v0, 0xbfb8aa3b, v153
	v_exp_f32_e32 v141, v0
	v_lshlrev_b32_e32 v132, 16, v144
	v_add_f32_e32 v133, 1.0, v133
	v_rcp_f32_e32 v170, v133
	v_add_f32_e32 v133, 1.0, v141
	v_rcp_f32_e32 v171, v133
	v_and_b32_e32 v133, 0xffff0000, v144
	v_lshlrev_b32_e32 v144, 16, v140
	v_and_b32_e32 v145, 0xffff0000, v140
	v_pk_mul_f32 v[140:141], v[122:123], v[132:133]
	v_lshlrev_b32_e32 v176, 16, v143
	v_pk_fma_f32 v[140:141], v[118:119], v[172:173], v[140:141]
	v_and_b32_e32 v177, 0xffff0000, v143
	v_pk_fma_f32 v[172:173], v[126:127], v[144:145], v[140:141]
	v_lshlrev_b32_e32 v174, 16, v131
	v_mul_f32_e32 v140, 0xbfb8aa3b, v172
	v_exp_f32_e32 v140, v140
	v_mul_f32_e32 v141, 0xbfb8aa3b, v173
	v_exp_f32_e32 v141, v141
	v_and_b32_e32 v175, 0xffff0000, v131
	v_add_f32_e32 v140, 1.0, v140
	v_pk_mul_f32 v[178:179], v[112:113], v[176:177]
	v_pk_mul_f32 v[170:171], v[152:153], v[170:171]
	v_rcp_f32_e32 v152, v140
	v_add_f32_e32 v153, 1.0, v141
	v_lshlrev_b32_e32 v140, 16, v139
	v_and_b32_e32 v141, 0xffff0000, v139
	v_pk_fma_f32 v[174:175], v[104:105], v[174:175], v[178:179]
	v_rcp_f32_e32 v153, v153
	v_pk_fma_f32 v[174:175], v[116:117], v[140:141], v[174:175]
	v_pk_mul_f32 v[184:185], v[124:125], v[150:151]
	v_mul_f32_e32 v131, 0xbfb8aa3b, v174
	v_exp_f32_e32 v131, v131
	v_mul_f32_e32 v139, 0xbfb8aa3b, v175
	v_exp_f32_e32 v139, v139
	v_pk_mul_f32 v[172:173], v[172:173], v[152:153]
	v_add_f32_e32 v131, 1.0, v131
	v_rcp_f32_e32 v178, v131
	v_add_f32_e32 v131, 1.0, v139
	v_rcp_f32_e32 v179, v131
	v_and_b32_e32 v131, 0xffff0000, v142
	v_lshlrev_b32_e32 v152, 16, v138
	v_and_b32_e32 v153, 0xffff0000, v138
	v_pk_mul_f32 v[174:175], v[174:175], v[178:179]
	v_lshlrev_b32_e32 v178, 16, v130
	v_and_b32_e32 v179, 0xffff0000, v130
	v_lshlrev_b32_e32 v130, 16, v142
	v_pk_mul_f32 v[138:139], v[110:111], v[130:131]
	v_pk_fma_f32 v[184:185], v[120:121], v[154:155], v[184:185]
	v_pk_fma_f32 v[138:139], v[102:103], v[178:179], v[138:139]
	v_lshlrev_b32_e32 v154, 16, v137
	v_pk_fma_f32 v[138:139], v[114:115], v[152:153], v[138:139]
	v_and_b32_e32 v155, 0xffff0000, v137
	v_mul_f32_e32 v142, 0xbfb8aa3b, v138
	v_mul_f32_e32 v143, 0xbfb8aa3b, v139
	v_exp_f32_e32 v142, v142
	v_exp_f32_e32 v143, v143
	v_pk_fma_f32 v[184:185], v[128:129], v[154:155], v[184:185]
	v_pk_mul_f32 v[192:193], v[112:113], v[140:141]
	v_mul_f32_e32 v137, 0xbfb8aa3b, v184
	v_exp_f32_e32 v137, v137
	v_mul_f32_e32 v186, 0xbfb8aa3b, v185
	v_add_f32_e32 v142, 1.0, v142
	v_add_f32_e32 v143, 1.0, v143
	v_exp_f32_e32 v187, v186
	v_rcp_f32_e32 v142, v142
	v_rcp_f32_e32 v143, v143
	v_add_f32_e32 v137, 1.0, v137
	v_rcp_f32_e32 v186, v137
	v_add_f32_e32 v137, 1.0, v187
	v_rcp_f32_e32 v187, v137
	v_pk_mul_f32 v[188:189], v[138:139], v[142:143]
	v_lshlrev_b32_e32 v142, 16, v136
	v_and_b32_e32 v143, 0xffff0000, v136
	v_pk_mul_f32 v[136:137], v[122:123], v[144:145]
	v_lshlrev_b32_e32 v138, 16, v135
	v_pk_fma_f32 v[132:133], v[118:119], v[132:133], v[136:137]
	v_and_b32_e32 v139, 0xffff0000, v135
	v_pk_fma_f32 v[132:133], v[126:127], v[142:143], v[132:133]
	v_pk_fma_f32 v[176:177], v[104:105], v[176:177], v[192:193]
	v_mul_f32_e32 v136, 0xbfb8aa3b, v132
	v_mul_f32_e32 v137, 0xbfb8aa3b, v133
	v_exp_f32_e32 v136, v136
	v_exp_f32_e32 v137, v137
	v_pk_fma_f32 v[176:177], v[116:117], v[138:139], v[176:177]
	v_pk_mul_f32 v[190:191], v[188:189], v[188:189]
	v_add_f32_e32 v136, 1.0, v136
	v_add_f32_e32 v137, 1.0, v137
	v_mul_f32_e32 v135, 0xbfb8aa3b, v176
	v_rcp_f32_e32 v136, v136
	v_rcp_f32_e32 v137, v137
	v_exp_f32_e32 v135, v135
	v_mul_f32_e32 v192, 0xbfb8aa3b, v177
	v_exp_f32_e32 v206, v192
	v_pk_mul_f32 v[192:193], v[132:133], v[136:137]
	v_add_f32_e32 v132, 1.0, v135
	v_lshlrev_b32_e32 v136, 16, v134
	v_and_b32_e32 v137, 0xffff0000, v134
	v_pk_mul_f32 v[134:135], v[110:111], v[152:153]
	v_add_f32_e32 v133, 1.0, v206
	v_pk_fma_f32 v[130:131], v[102:103], v[130:131], v[134:135]
	v_rcp_f32_e32 v132, v132
	v_pk_fma_f32 v[130:131], v[114:115], v[136:137], v[130:131]
	v_rcp_f32_e32 v133, v133
	v_mul_f32_e32 v134, 0xbfb8aa3b, v130
	v_mul_f32_e32 v135, 0xbfb8aa3b, v131
	v_exp_f32_e32 v134, v134
	v_exp_f32_e32 v135, v135
	v_pk_mul_f32 v[176:177], v[176:177], v[132:133]
	v_pk_mul_f32 v[178:179], v[174:175], v[174:175]
	v_add_f32_e32 v134, 1.0, v134
	v_add_f32_e32 v135, 1.0, v135
	v_rcp_f32_e32 v134, v134
	v_rcp_f32_e32 v135, v135
	v_pk_mul_f32 v[132:133], v[176:177], v[176:177]
	v_mov_b32_e32 v209, v190
	v_pk_mul_f32 v[182:183], v[172:173], v[172:173]
	v_pk_mul_f32 v[130:131], v[130:131], v[134:135]
	v_pk_mul_f32 v[206:207], v[192:193], v[192:193]
	v_pk_mul_f32 v[134:135], v[130:131], v[130:131]
	v_pk_mul_f32 v[184:185], v[184:185], v[186:187]
	v_mov_b32_e32 v208, v134
	v_mov_b32_e32 v190, v135
	v_pk_add_f32 v[134:135], v[208:209], v[190:191]
	v_mov_b32_e32 v190, v132
	v_mov_b32_e32 v191, v178
	v_pk_add_f32 v[134:135], v[190:191], v[134:135]
	v_mov_b32_e32 v178, v133
	v_pk_add_f32 v[132:133], v[178:179], v[134:135]
	v_mov_b32_e32 v134, v206
	v_mov_b32_e32 v135, v182
	v_pk_mul_f32 v[180:181], v[170:171], v[170:171]
	v_pk_mul_f32 v[186:187], v[184:185], v[184:185]
	v_pk_add_f32 v[132:133], v[134:135], v[132:133]
	v_mov_b32_e32 v182, v207
	v_pk_add_f32 v[132:133], v[182:183], v[132:133]
	v_mov_b32_e32 v134, v186
	v_mov_b32_e32 v135, v180
	v_pk_add_f32 v[132:133], v[134:135], v[132:133]
	v_mov_b32_e32 v180, v187
	v_pk_add_f32 v[132:133], v[180:181], v[132:133]
	s_mov_b32 s2, 0x358637bd
	v_addc_co_u32_e32 v35, vcc, 0, v35, vcc
	v_mov_b32_dpp v135, v133 quad_perm:[1,0,3,2] row_mask:0xf bank_mask:0xf bound_ctrl:1
	v_mov_b32_dpp v134, v132 quad_perm:[1,0,3,2] row_mask:0xf bank_mask:0xf bound_ctrl:1
	v_pk_add_f32 v[132:133], v[132:133], v[134:135]
	v_sub_u32_e32 v203, 63, v168
	v_lshl_add_u32 v0, v167, 1, v146
	v_mov_b32_dpp v135, v133 quad_perm:[2,3,0,1] row_mask:0xf bank_mask:0xf bound_ctrl:1
	v_mov_b32_dpp v134, v132 quad_perm:[2,3,0,1] row_mask:0xf bank_mask:0xf bound_ctrl:1
	v_pk_add_f32 v[132:133], v[132:133], v[134:135]
	global_load_dwordx4 v[42:45], v[32:33], off
	s_nop 0
	global_load_dwordx4 v[30:33], v[30:31], off offset:16
	v_mov_b32_dpp v135, v133 row_half_mirror row_mask:0xf bank_mask:0xf bound_ctrl:1
	v_mov_b32_dpp v134, v132 row_half_mirror row_mask:0xf bank_mask:0xf bound_ctrl:1
	v_pk_add_f32 v[132:133], v[132:133], v[134:135]
	global_load_dwordx4 v[46:49], v[34:35], off
	s_nop 0
	global_load_dwordx4 v[34:37], v[36:37], off offset:16
	v_mov_b32_dpp v135, v133 row_mirror row_mask:0xf bank_mask:0xf bound_ctrl:1
	v_mov_b32_dpp v134, v132 row_mirror row_mask:0xf bank_mask:0xf bound_ctrl:1
	v_pk_add_f32 v[132:133], v[132:133], v[134:135]
	v_and_b32_e32 v160, 63, v148
	v_pk_add_f32 v[134:135], v[132:133], s[2:3] op_sel_hi:[1,0]
	s_nop 0
	v_mul_f32_e32 v132, 0x4b800000, v135
	v_cmp_gt_f32_e32 vcc, s72, v135
	s_nop 1
	v_cndmask_b32_e32 v132, v135, v132, vcc
	v_rsq_f32_e32 v135, v132
	v_cndmask_b32_e64 v132, v203, v168, s[44:45]
	v_mad_u64_u32 v[132:133], s[0:1], v132, s14, v[0:1]
	v_mul_f32_e32 v133, 0x45800000, v135
	v_cndmask_b32_e32 v178, v135, v133, vcc
	v_mul_f32_e32 v133, 0x4b800000, v134
	v_cmp_gt_f32_e32 vcc, s72, v134
	v_pk_mul_f32 v[180:181], v[188:189], v[178:179] op_sel_hi:[1,0]
	v_pk_mul_f32 v[174:175], v[174:175], v[178:179] op_sel_hi:[1,0]
	v_cndmask_b32_e32 v133, v134, v133, vcc
	v_rsq_f32_e32 v133, v133
	v_pk_mul_f32 v[172:173], v[172:173], v[178:179] op_sel_hi:[1,0]
	v_pk_mul_f32 v[178:179], v[170:171], v[178:179] op_sel_hi:[1,0]
	v_cvt_pk_bf16_f32 v170, v180, v181
	v_mul_f32_e32 v134, 0x45800000, v133
	v_cvt_pk_bf16_f32 v171, v174, v175
	v_cvt_pk_bf16_f32 v172, v172, v173
	v_cvt_pk_bf16_f32 v173, v178, v179
	v_cndmask_b32_e32 v134, v133, v134, vcc
	ds_write_b128 v132, v[170:173]
	v_pk_mul_f32 v[130:131], v[130:131], v[134:135] op_sel_hi:[1,0]
	v_pk_mul_f32 v[172:173], v[176:177], v[134:135] op_sel_hi:[1,0]
	v_pk_mul_f32 v[174:175], v[192:193], v[134:135] op_sel_hi:[1,0]
	v_pk_mul_f32 v[134:135], v[184:185], v[134:135] op_sel_hi:[1,0]
	v_or_b32_e32 v133, 1, v168
	v_cvt_pk_bf16_f32 v171, v172, v173
	v_cvt_pk_bf16_f32 v173, v134, v135
	v_pk_mul_f32 v[134:135], v[124:125], v[154:155]
	v_sub_u32_e32 v170, 63, v133
	v_pk_fma_f32 v[134:135], v[120:121], v[150:151], v[134:135]
	v_lshlrev_b32_e32 v150, 16, v109
	v_and_b32_e32 v151, 0xffff0000, v109
	v_cndmask_b32_e64 v133, v170, v133, s[44:45]
	v_pk_fma_f32 v[134:135], v[128:129], v[150:151], v[134:135]
	v_pk_mul_f32 v[124:125], v[124:125], v[150:151]
	v_cvt_pk_bf16_f32 v170, v130, v131
	v_mad_u64_u32 v[130:131], s[0:1], v133, s14, v[0:1]
	v_mul_f32_e32 v109, 0xbfb8aa3b, v134
	v_pk_fma_f32 v[120:121], v[120:121], v[154:155], v[124:125]
	v_lshlrev_b32_e32 v124, 16, v101
	v_and_b32_e32 v125, 0xffff0000, v101
	v_exp_f32_e32 v109, v109
	v_mul_f32_e32 v131, 0xbfb8aa3b, v135
	v_pk_fma_f32 v[120:121], v[128:129], v[124:125], v[120:121]
	v_exp_f32_e32 v131, v131
	v_mul_f32_e32 v101, 0xbfb8aa3b, v120
	v_exp_f32_e32 v101, v101
	v_mul_f32_e32 v124, 0xbfb8aa3b, v121
	v_exp_f32_e32 v125, v124
	v_cvt_pk_bf16_f32 v172, v174, v175
	v_add_f32_e32 v109, 1.0, v109
	ds_write_b128 v130, v[170:173]
	v_rcp_f32_e32 v170, v109
	v_add_f32_e32 v109, 1.0, v131
	v_rcp_f32_e32 v171, v109
	v_lshlrev_b32_e32 v172, 16, v108
	v_and_b32_e32 v173, 0xffff0000, v108
	v_pk_mul_f32 v[108:109], v[122:123], v[142:143]
	v_add_f32_e32 v101, 1.0, v101
	v_pk_fma_f32 v[108:109], v[118:119], v[144:145], v[108:109]
	v_rcp_f32_e32 v124, v101
	v_add_f32_e32 v101, 1.0, v125
	v_pk_fma_f32 v[108:109], v[126:127], v[172:173], v[108:109]
	v_rcp_f32_e32 v125, v101
	v_mul_f32_e32 v131, 0xbfb8aa3b, v108
	v_exp_f32_e32 v131, v131
	v_mul_f32_e32 v133, 0xbfb8aa3b, v109
	v_exp_f32_e32 v133, v133
	v_pk_mul_f32 v[174:175], v[112:113], v[138:139]
	v_pk_mul_f32 v[134:135], v[134:135], v[170:171]
	v_lshlrev_b32_e32 v170, 16, v107
	v_and_b32_e32 v171, 0xffff0000, v107
	v_pk_fma_f32 v[140:141], v[104:105], v[140:141], v[174:175]
	v_pk_mul_f32 v[120:121], v[120:121], v[124:125]
	v_lshlrev_b32_e32 v124, 16, v100
	v_and_b32_e32 v125, 0xffff0000, v100
	v_pk_mul_f32 v[100:101], v[122:123], v[172:173]
	v_pk_fma_f32 v[140:141], v[116:117], v[170:171], v[140:141]
	v_pk_fma_f32 v[100:101], v[118:119], v[142:143], v[100:101]
	v_add_f32_e32 v131, 1.0, v131
	v_mul_f32_e32 v107, 0xbfb8aa3b, v140
	v_pk_fma_f32 v[100:101], v[126:127], v[124:125], v[100:101]
	v_rcp_f32_e32 v144, v131
	v_add_f32_e32 v131, 1.0, v133
	v_exp_f32_e32 v107, v107
	v_mul_f32_e32 v133, 0xbfb8aa3b, v141
	v_mul_f32_e32 v118, 0xbfb8aa3b, v100
	v_exp_f32_e32 v133, v133
	v_exp_f32_e32 v122, v118
	v_mul_f32_e32 v118, 0xbfb8aa3b, v101
	v_exp_f32_e32 v123, v118
	v_pk_mul_f32 v[112:113], v[112:113], v[170:171]
	v_lshlrev_b32_e32 v124, 16, v99
	v_and_b32_e32 v125, 0xffff0000, v99
	v_pk_fma_f32 v[104:105], v[104:105], v[138:139], v[112:113]
	v_add_f32_e32 v107, 1.0, v107
	v_pk_fma_f32 v[104:105], v[116:117], v[124:125], v[104:105]
	v_rcp_f32_e32 v174, v107
	v_add_f32_e32 v107, 1.0, v133
	v_mul_f32_e32 v99, 0xbfb8aa3b, v104
	v_rcp_f32_e32 v175, v107
	v_add_f32_e32 v122, 1.0, v122
	v_add_f32_e32 v123, 1.0, v123
	v_exp_f32_e32 v99, v99
	v_mul_f32_e32 v112, 0xbfb8aa3b, v105
	v_rcp_f32_e32 v122, v122
	v_rcp_f32_e32 v123, v123
	v_exp_f32_e32 v116, v112
	v_pk_mul_f32 v[140:141], v[140:141], v[174:175]
	v_lshlrev_b32_e32 v174, 16, v106
	v_and_b32_e32 v175, 0xffff0000, v106
	v_pk_mul_f32 v[106:107], v[110:111], v[136:137]
	v_add_f32_e32 v99, 1.0, v99
	v_pk_fma_f32 v[106:107], v[102:103], v[152:153], v[106:107]
	v_pk_mul_f32 v[112:113], v[100:101], v[122:123]
	v_rcp_f32_e32 v100, v99
	v_add_f32_e32 v101, 1.0, v116
	v_lshlrev_b32_e32 v116, 16, v98
	v_and_b32_e32 v117, 0xffff0000, v98
	v_pk_mul_f32 v[98:99], v[110:111], v[174:175]
	v_pk_fma_f32 v[106:107], v[114:115], v[174:175], v[106:107]
	v_pk_fma_f32 v[98:99], v[102:103], v[136:137], v[98:99]
	v_rcp_f32_e32 v145, v131
	v_mul_f32_e32 v131, 0xbfb8aa3b, v106
	v_pk_fma_f32 v[98:99], v[114:115], v[116:117], v[98:99]
	v_exp_f32_e32 v131, v131
	v_mul_f32_e32 v133, 0xbfb8aa3b, v107
	v_mul_f32_e32 v102, 0xbfb8aa3b, v98
	v_mul_f32_e32 v103, 0xbfb8aa3b, v99
	v_exp_f32_e32 v133, v133
	v_exp_f32_e32 v102, v102
	v_exp_f32_e32 v103, v103
	v_add_f32_e32 v131, 1.0, v131
	v_rcp_f32_e32 v178, v131
	v_add_f32_e32 v131, 1.0, v133
	v_add_f32_e32 v102, 1.0, v102
	v_add_f32_e32 v103, 1.0, v103
	v_rcp_f32_e32 v179, v131
	v_rcp_f32_e32 v102, v102
	v_rcp_f32_e32 v103, v103
	v_rcp_f32_e32 v101, v101
	v_pk_mul_f32 v[106:107], v[106:107], v[178:179]
	v_pk_mul_f32 v[152:153], v[140:141], v[140:141]
	v_pk_mul_f32 v[114:115], v[98:99], v[102:103]
	v_pk_mul_f32 v[128:129], v[106:107], v[106:107]
	v_pk_mul_f32 v[104:105], v[104:105], v[100:101]
	v_pk_mul_f32 v[98:99], v[114:115], v[114:115]
	v_pk_mul_f32 v[100:101], v[104:105], v[104:105]
	v_mov_b32_e32 v102, v98
	v_mov_b32_e32 v103, v128
	v_mov_b32_e32 v128, v99
	v_pk_mul_f32 v[108:109], v[108:109], v[144:145]
	v_pk_add_f32 v[98:99], v[102:103], v[128:129]
	v_mov_b32_e32 v102, v100
	v_mov_b32_e32 v103, v152
	v_pk_mul_f32 v[144:145], v[108:109], v[108:109]
	v_pk_mul_f32 v[110:111], v[112:113], v[112:113]
	v_pk_add_f32 v[98:99], v[102:103], v[98:99]
	v_mov_b32_e32 v152, v101
	v_pk_add_f32 v[98:99], v[152:153], v[98:99]
	v_mov_b32_e32 v100, v110
	v_mov_b32_e32 v101, v144
	v_pk_mul_f32 v[176:177], v[134:135], v[134:135]
	v_pk_mul_f32 v[118:119], v[120:121], v[120:121]
	v_pk_add_f32 v[98:99], v[100:101], v[98:99]
	v_mov_b32_e32 v144, v111
	v_pk_add_f32 v[98:99], v[144:145], v[98:99]
	v_mov_b32_e32 v100, v118
	v_mov_b32_e32 v101, v176
	v_pk_add_f32 v[98:99], v[100:101], v[98:99]
	v_mov_b32_e32 v176, v119
	v_pk_add_f32 v[98:99], v[176:177], v[98:99]
	v_or_b32_e32 v131, 2, v168
	v_sub_u32_e32 v133, 63, v131
	v_mov_b32_dpp v101, v99 quad_perm:[1,0,3,2] row_mask:0xf bank_mask:0xf bound_ctrl:1
	v_mov_b32_dpp v100, v98 quad_perm:[1,0,3,2] row_mask:0xf bank_mask:0xf bound_ctrl:1
	v_pk_add_f32 v[98:99], v[98:99], v[100:101]
	v_lshlrev_b32_e32 v118, 16, v89
	v_and_b32_e32 v119, 0xffff0000, v89
	v_mov_b32_dpp v101, v99 quad_perm:[2,3,0,1] row_mask:0xf bank_mask:0xf bound_ctrl:1
	v_mov_b32_dpp v100, v98 quad_perm:[2,3,0,1] row_mask:0xf bank_mask:0xf bound_ctrl:1
	v_pk_add_f32 v[98:99], v[98:99], v[100:101]
	s_nop 1
	v_mov_b32_dpp v101, v99 row_half_mirror row_mask:0xf bank_mask:0xf bound_ctrl:1
	v_mov_b32_dpp v100, v98 row_half_mirror row_mask:0xf bank_mask:0xf bound_ctrl:1
	v_pk_add_f32 v[98:99], v[98:99], v[100:101]
	s_nop 1
	v_mov_b32_dpp v101, v99 row_mirror row_mask:0xf bank_mask:0xf bound_ctrl:1
	v_mov_b32_dpp v100, v98 row_mirror row_mask:0xf bank_mask:0xf bound_ctrl:1
	v_pk_add_f32 v[98:99], v[98:99], v[100:101]
	s_nop 0
	v_pk_add_f32 v[100:101], v[98:99], s[2:3] op_sel_hi:[1,0]
	v_cndmask_b32_e64 v99, v133, v131, s[44:45]
	v_mul_f32_e32 v98, 0x4b800000, v101
	v_cmp_gt_f32_e32 vcc, s72, v101
	v_mad_u64_u32 v[102:103], s[0:1], v99, s14, v[0:1]
	s_nop 0
	v_cndmask_b32_e32 v98, v101, v98, vcc
	v_rsq_f32_e32 v98, v98
	v_mul_f32_e32 v101, 0x4b800000, v100
	v_and_b32_e32 v133, 0xffff0000, v54
	v_mul_f32_e32 v99, 0x45800000, v98
	v_cndmask_b32_e32 v98, v98, v99, vcc
	v_cmp_gt_f32_e32 vcc, s72, v100
	v_pk_mul_f32 v[106:107], v[106:107], v[98:99] op_sel_hi:[1,0]
	v_pk_mul_f32 v[110:111], v[140:141], v[98:99] op_sel_hi:[1,0]
	v_cndmask_b32_e32 v100, v100, v101, vcc
	v_rsq_f32_e32 v103, v100
	v_pk_mul_f32 v[108:109], v[108:109], v[98:99] op_sel_hi:[1,0]
	v_pk_mul_f32 v[116:117], v[134:135], v[98:99] op_sel_hi:[1,0]
	v_cvt_pk_bf16_f32 v98, v106, v107
	v_cvt_pk_bf16_f32 v99, v110, v111
	v_cvt_pk_bf16_f32 v100, v108, v109
	v_cvt_pk_bf16_f32 v101, v116, v117
	ds_write_b128 v102, v[98:101]
	v_mul_f32_e32 v98, 0x45800000, v103
	v_cndmask_b32_e32 v98, v103, v98, vcc
	v_pk_mul_f32 v[100:101], v[114:115], v[98:99] op_sel_hi:[1,0]
	v_pk_mul_f32 v[104:105], v[104:105], v[98:99] op_sel_hi:[1,0]
	v_pk_mul_f32 v[106:107], v[112:113], v[98:99] op_sel_hi:[1,0]
	v_pk_mul_f32 v[108:109], v[120:121], v[98:99] op_sel_hi:[1,0]
	v_or_b32_e32 v98, 3, v168
	v_sub_u32_e32 v99, 63, v98
	v_lshlrev_b32_e32 v110, 16, v97
	v_and_b32_e32 v111, 0xffff0000, v97
	v_cndmask_b32_e64 v103, v99, v98, s[44:45]
	v_cvt_pk_bf16_f32 v98, v100, v101
	v_cvt_pk_bf16_f32 v99, v104, v105
	v_lshlrev_b32_e32 v100, 16, v85
	v_and_b32_e32 v101, 0xffff0000, v85
	s_waitcnt vmcnt(8)
	v_pk_mul_f32 v[104:105], v[76:77], v[110:111]
	v_lshlrev_b32_e32 v116, 16, v84
	v_pk_fma_f32 v[100:101], v[72:73], v[100:101], v[104:105]
	v_lshlrev_b32_e32 v104, 16, v93
	v_and_b32_e32 v105, 0xffff0000, v93
	s_waitcnt vmcnt(6)
	v_pk_fma_f32 v[112:113], v[80:81], v[104:105], v[100:101]
	v_and_b32_e32 v117, 0xffff0000, v84
	v_mul_f32_e32 v85, 0xbfb8aa3b, v112
	v_exp_f32_e32 v85, v85
	v_mul_f32_e32 v93, 0xbfb8aa3b, v113
	v_exp_f32_e32 v93, v93
	v_lshlrev_b32_e32 v84, 16, v96
	v_add_f32_e32 v85, 1.0, v85
	v_rcp_f32_e32 v114, v85
	v_and_b32_e32 v85, 0xffff0000, v96
	v_cvt_pk_bf16_f32 v100, v106, v107
	v_add_f32_e32 v97, 1.0, v93
	v_lshlrev_b32_e32 v106, 16, v92
	v_and_b32_e32 v107, 0xffff0000, v92
	v_pk_mul_f32 v[92:93], v[74:75], v[84:85]
	v_rcp_f32_e32 v115, v97
	v_pk_fma_f32 v[92:93], v[70:71], v[116:117], v[92:93]
	v_lshlrev_b32_e32 v116, 16, v90
	v_pk_fma_f32 v[92:93], v[78:79], v[106:107], v[92:93]
	v_pk_mul_f32 v[120:121], v[112:113], v[114:115]
	v_mul_f32_e32 v96, 0xbfb8aa3b, v92
	v_mul_f32_e32 v101, 0xbfb8aa3b, v93
	v_exp_f32_e32 v96, v96
	v_exp_f32_e32 v101, v101
	v_lshlrev_b32_e32 v114, 16, v82
	v_and_b32_e32 v115, 0xffff0000, v82
	v_add_f32_e32 v96, 1.0, v96
	v_add_f32_e32 v97, 1.0, v101
	v_rcp_f32_e32 v96, v96
	v_rcp_f32_e32 v97, v97
	v_cvt_pk_bf16_f32 v101, v108, v109
	v_lshlrev_b32_e32 v108, 16, v91
	v_and_b32_e32 v109, 0xffff0000, v91
	v_pk_mul_f32 v[124:125], v[92:93], v[96:97]
	v_lshlrev_b32_e32 v96, 16, v95
	v_and_b32_e32 v97, 0xffff0000, v95
	v_lshlrev_b32_e32 v92, 16, v83
	v_and_b32_e32 v93, 0xffff0000, v83
	v_pk_mul_f32 v[112:113], v[64:65], v[96:97]
	v_lshlrev_b32_e32 v82, 16, v94
	v_pk_fma_f32 v[92:93], v[60:61], v[92:93], v[112:113]
	v_and_b32_e32 v117, 0xffff0000, v90
	v_pk_fma_f32 v[92:93], v[68:69], v[108:109], v[92:93]
	v_pk_mul_f32 v[136:137], v[64:65], v[108:109]
	v_mul_f32_e32 v83, 0xbfb8aa3b, v92
	v_exp_f32_e32 v83, v83
	v_mul_f32_e32 v91, 0xbfb8aa3b, v93
	v_exp_f32_e32 v91, v91
	v_pk_fma_f32 v[96:97], v[60:61], v[96:97], v[136:137]
	v_add_f32_e32 v83, 1.0, v83
	v_rcp_f32_e32 v112, v83
	v_add_f32_e32 v83, 1.0, v91
	v_rcp_f32_e32 v113, v83
	v_and_b32_e32 v83, 0xffff0000, v94
	v_pk_mul_f32 v[90:91], v[62:63], v[82:83]
	v_pk_mul_f32 v[126:127], v[124:125], v[124:125]
	v_pk_fma_f32 v[90:91], v[58:59], v[114:115], v[90:91]
	v_pk_mul_f32 v[122:123], v[120:121], v[120:121]
	v_pk_fma_f32 v[90:91], v[66:67], v[116:117], v[90:91]
	s_nop 0
	v_mul_f32_e32 v94, 0xbfb8aa3b, v90
	v_exp_f32_e32 v114, v94
	v_mul_f32_e32 v94, 0xbfb8aa3b, v91
	v_exp_f32_e32 v115, v94
	v_pk_mul_f32 v[94:95], v[92:93], v[112:113]
	v_pk_mul_f32 v[112:113], v[76:77], v[104:105]
	v_add_f32_e32 v92, 1.0, v114
	v_pk_fma_f32 v[110:111], v[72:73], v[110:111], v[112:113]
	v_add_f32_e32 v93, 1.0, v115
	v_pk_fma_f32 v[110:111], v[80:81], v[118:119], v[110:111]
	v_lshlrev_b32_e32 v114, 16, v88
	v_mul_f32_e32 v89, 0xbfb8aa3b, v110
	v_exp_f32_e32 v89, v89
	v_mul_f32_e32 v112, 0xbfb8aa3b, v111
	v_exp_f32_e32 v113, v112
	v_and_b32_e32 v115, 0xffff0000, v88
	v_add_f32_e32 v89, 1.0, v89
	v_rcp_f32_e32 v112, v89
	v_add_f32_e32 v89, 1.0, v113
	v_rcp_f32_e32 v113, v89
	v_pk_mul_f32 v[88:89], v[74:75], v[106:107]
	v_rcp_f32_e32 v92, v92
	v_pk_fma_f32 v[84:85], v[70:71], v[84:85], v[88:89]
	v_pk_mul_f32 v[134:135], v[110:111], v[112:113]
	v_pk_fma_f32 v[84:85], v[78:79], v[114:115], v[84:85]
	v_lshlrev_b32_e32 v112, 16, v87
	v_mul_f32_e32 v88, 0xbfb8aa3b, v84
	v_exp_f32_e32 v110, v88
	v_mul_f32_e32 v88, 0xbfb8aa3b, v85
	v_exp_f32_e32 v111, v88
	v_and_b32_e32 v113, 0xffff0000, v87
	v_pk_fma_f32 v[96:97], v[68:69], v[112:113], v[96:97]
	v_add_f32_e32 v110, 1.0, v110
	v_add_f32_e32 v111, 1.0, v111
	v_mul_f32_e32 v87, 0xbfb8aa3b, v96
	v_rcp_f32_e32 v110, v110
	v_rcp_f32_e32 v111, v111
	v_exp_f32_e32 v87, v87
	v_mul_f32_e32 v131, 0xbfb8aa3b, v97
	v_exp_f32_e32 v131, v131
	v_pk_mul_f32 v[136:137], v[84:85], v[110:111]
	v_add_f32_e32 v84, 1.0, v87
	v_lshlrev_b32_e32 v110, 16, v86
	v_and_b32_e32 v111, 0xffff0000, v86
	v_pk_mul_f32 v[86:87], v[62:63], v[116:117]
	v_rcp_f32_e32 v93, v93
	v_pk_fma_f32 v[82:83], v[58:59], v[82:83], v[86:87]
	v_add_f32_e32 v85, 1.0, v131
	v_pk_fma_f32 v[82:83], v[66:67], v[110:111], v[82:83]
	v_rcp_f32_e32 v84, v84
	v_mul_f32_e32 v86, 0xbfb8aa3b, v82
	v_mul_f32_e32 v87, 0xbfb8aa3b, v83
	v_exp_f32_e32 v86, v86
	v_exp_f32_e32 v87, v87
	v_rcp_f32_e32 v85, v85
	v_pk_mul_f32 v[90:91], v[90:91], v[92:93]
	v_add_f32_e32 v86, 1.0, v86
	v_add_f32_e32 v87, 1.0, v87
	v_rcp_f32_e32 v86, v86
	v_rcp_f32_e32 v87, v87
	v_pk_mul_f32 v[92:93], v[90:91], v[90:91]
	v_pk_mul_f32 v[140:141], v[96:97], v[84:85]
	v_pk_mul_f32 v[128:129], v[94:95], v[94:95]
	v_pk_mul_f32 v[86:87], v[82:83], v[86:87]
	v_pk_mul_f32 v[84:85], v[140:141], v[140:141]
	v_pk_mul_f32 v[82:83], v[86:87], v[86:87]
	v_mov_b32_e32 v97, v92
	v_mov_b32_e32 v96, v82
	v_mov_b32_e32 v92, v83
	v_pk_add_f32 v[82:83], v[96:97], v[92:93]
	v_mov_b32_e32 v92, v84
	v_mov_b32_e32 v93, v128
	v_pk_mul_f32 v[138:139], v[136:137], v[136:137]
	v_pk_add_f32 v[82:83], v[92:93], v[82:83]
	v_mov_b32_e32 v128, v85
	v_pk_add_f32 v[82:83], v[128:129], v[82:83]
	v_mov_b32_e32 v84, v138
	v_mov_b32_e32 v85, v126
	v_pk_mul_f32 v[88:89], v[134:135], v[134:135]
	v_pk_add_f32 v[82:83], v[84:85], v[82:83]
	v_mov_b32_e32 v126, v139
	v_pk_add_f32 v[82:83], v[126:127], v[82:83]
	v_mov_b32_e32 v84, v88
	v_mov_b32_e32 v85, v122
	v_pk_add_f32 v[82:83], v[84:85], v[82:83]
	v_mov_b32_e32 v122, v89
	v_pk_add_f32 v[82:83], v[122:123], v[82:83]
	v_mad_u64_u32 v[96:97], s[0:1], v103, s14, v[0:1]
	s_nop 0
	v_mov_b32_dpp v85, v83 quad_perm:[1,0,3,2] row_mask:0xf bank_mask:0xf bound_ctrl:1
	v_mov_b32_dpp v84, v82 quad_perm:[1,0,3,2] row_mask:0xf bank_mask:0xf bound_ctrl:1
	v_pk_add_f32 v[82:83], v[82:83], v[84:85]
	ds_write_b128 v96, v[98:101]
	v_pk_mul_f32 v[126:127], v[64:65], v[112:113]
	v_mov_b32_dpp v85, v83 quad_perm:[2,3,0,1] row_mask:0xf bank_mask:0xf bound_ctrl:1
	v_mov_b32_dpp v84, v82 quad_perm:[2,3,0,1] row_mask:0xf bank_mask:0xf bound_ctrl:1
	v_pk_add_f32 v[82:83], v[82:83], v[84:85]
	v_pk_fma_f32 v[108:109], v[60:61], v[108:109], v[126:127]
	s_movk_i32 s0, 0x48
	v_mov_b32_dpp v85, v83 row_half_mirror row_mask:0xf bank_mask:0xf bound_ctrl:1
	v_mov_b32_dpp v84, v82 row_half_mirror row_mask:0xf bank_mask:0xf bound_ctrl:1
	v_pk_add_f32 v[82:83], v[82:83], v[84:85]
	s_nop 1
	v_mov_b32_dpp v85, v83 row_mirror row_mask:0xf bank_mask:0xf bound_ctrl:1
	v_mov_b32_dpp v84, v82 row_mirror row_mask:0xf bank_mask:0xf bound_ctrl:1
	v_pk_add_f32 v[82:83], v[82:83], v[84:85]
	s_nop 0
	v_pk_add_f32 v[122:123], v[82:83], s[2:3] op_sel_hi:[1,0]
	s_nop 0
	v_mul_f32_e32 v82, 0x4b800000, v123
	v_cmp_gt_f32_e32 vcc, s72, v123
	s_nop 1
	v_cndmask_b32_e32 v82, v123, v82, vcc
	v_rsq_f32_e32 v82, v82
	s_nop 0
	v_mul_f32_e32 v0, 0x45800000, v82
	v_cndmask_b32_e32 v0, v82, v0, vcc
	v_pk_mul_f32 v[92:93], v[90:91], v[0:1] op_sel_hi:[1,0]
	v_pk_mul_f32 v[88:89], v[94:95], v[0:1] op_sel_hi:[1,0]
	v_pk_mul_f32 v[84:85], v[124:125], v[0:1] op_sel_hi:[1,0]
	v_pk_mul_f32 v[82:83], v[120:121], v[0:1] op_sel_hi:[1,0]
	v_mul_f32_e32 v0, 0x4b800000, v122
	v_cmp_gt_f32_e32 vcc, s72, v122
	v_cvt_pk_bf16_f32 v98, v92, v93
	v_cvt_pk_bf16_f32 v99, v88, v89
	v_cndmask_b32_e32 v0, v122, v0, vcc
	v_rsq_f32_e32 v0, v0
	v_cvt_pk_bf16_f32 v100, v84, v85
	v_cvt_pk_bf16_f32 v101, v82, v83
	ds_write_b128 v132, v[98:101] offset:17408
	v_pk_mul_f32 v[100:101], v[76:77], v[118:119]
	v_mul_f32_e32 v90, 0x45800000, v0
	v_pk_fma_f32 v[100:101], v[72:73], v[104:105], v[100:101]
	v_lshlrev_b32_e32 v120, 16, v57
	v_and_b32_e32 v121, 0xffff0000, v57
	v_cndmask_b32_e32 v0, v0, v90, vcc
	v_pk_fma_f32 v[100:101], v[80:81], v[120:121], v[100:101]
	v_pk_mul_f32 v[98:99], v[86:87], v[0:1] op_sel_hi:[1,0]
	v_pk_mul_f32 v[94:95], v[140:141], v[0:1] op_sel_hi:[1,0]
	v_pk_mul_f32 v[90:91], v[136:137], v[0:1] op_sel_hi:[1,0]
	v_pk_mul_f32 v[86:87], v[134:135], v[0:1] op_sel_hi:[1,0]
	v_mul_f32_e32 v0, 0xbfb8aa3b, v100
	v_exp_f32_e32 v0, v0
	v_mul_f32_e32 v57, 0xbfb8aa3b, v101
	v_exp_f32_e32 v57, v57
	v_lshlrev_b32_e32 v124, 16, v56
	v_add_f32_e32 v0, 1.0, v0
	v_rcp_f32_e32 v122, v0
	v_add_f32_e32 v0, 1.0, v57
	v_and_b32_e32 v125, 0xffff0000, v56
	v_pk_mul_f32 v[56:57], v[74:75], v[114:115]
	v_rcp_f32_e32 v123, v0
	v_pk_fma_f32 v[56:57], v[70:71], v[106:107], v[56:57]
	v_lshlrev_b32_e32 v132, 16, v54
	v_pk_fma_f32 v[56:57], v[78:79], v[124:125], v[56:57]
	v_pk_mul_f32 v[76:77], v[76:77], v[120:121]
	v_mul_f32_e32 v97, 0xbfb8aa3b, v56
	v_exp_f32_e32 v97, v97
	v_mul_f32_e32 v103, 0xbfb8aa3b, v57
	v_exp_f32_e32 v103, v103
	v_pk_fma_f32 v[72:73], v[72:73], v[118:119], v[76:77]
	v_add_f32_e32 v0, 1.0, v97
	v_rcp_f32_e32 v106, v0
	v_add_f32_e32 v0, 1.0, v103
	v_rcp_f32_e32 v107, v0
	v_lshlrev_b32_e32 v76, 16, v53
	v_and_b32_e32 v77, 0xffff0000, v53
	v_pk_fma_f32 v[72:73], v[80:81], v[76:77], v[72:73]
	v_pk_mul_f32 v[56:57], v[56:57], v[106:107]
	v_lshlrev_b32_e32 v106, 16, v55
	v_and_b32_e32 v107, 0xffff0000, v55
	v_pk_fma_f32 v[108:109], v[68:69], v[106:107], v[108:109]
	v_mul_f32_e32 v53, 0xbfb8aa3b, v72
	v_mul_f32_e32 v0, 0xbfb8aa3b, v108
	v_exp_f32_e32 v0, v0
	v_mul_f32_e32 v55, 0xbfb8aa3b, v109
	v_exp_f32_e32 v55, v55
	v_exp_f32_e32 v53, v53
	v_add_f32_e32 v0, 1.0, v0
	v_rcp_f32_e32 v128, v0
	v_add_f32_e32 v0, 1.0, v55
	v_pk_mul_f32 v[54:55], v[62:63], v[110:111]
	v_rcp_f32_e32 v129, v0
	v_pk_fma_f32 v[54:55], v[58:59], v[116:117], v[54:55]
	v_mul_f32_e32 v76, 0xbfb8aa3b, v73
	v_pk_fma_f32 v[54:55], v[66:67], v[132:133], v[54:55]
	v_exp_f32_e32 v77, v76
	v_mul_f32_e32 v0, 0xbfb8aa3b, v54
	v_exp_f32_e32 v0, v0
	v_mul_f32_e32 v97, 0xbfb8aa3b, v55
	v_exp_f32_e32 v97, v97
	v_pk_mul_f32 v[64:65], v[64:65], v[106:107]
	v_add_f32_e32 v0, 1.0, v0
	v_rcp_f32_e32 v116, v0
	v_add_f32_e32 v0, 1.0, v97
	v_rcp_f32_e32 v117, v0
	v_add_f32_e32 v0, 1.0, v53
	v_rcp_f32_e32 v76, v0
	v_add_f32_e32 v0, 1.0, v77
	v_rcp_f32_e32 v77, v0
	v_pk_fma_f32 v[60:61], v[60:61], v[112:113], v[64:65]
	v_pk_mul_f32 v[54:55], v[54:55], v[116:117]
	v_pk_mul_f32 v[108:109], v[108:109], v[128:129]
	v_pk_mul_f32 v[72:73], v[72:73], v[76:77]
	v_lshlrev_b32_e32 v76, 16, v52
	v_and_b32_e32 v77, 0xffff0000, v52
	v_pk_mul_f32 v[52:53], v[74:75], v[124:125]
	v_pk_mul_f32 v[116:117], v[54:55], v[54:55]
	v_pk_fma_f32 v[52:53], v[70:71], v[114:115], v[52:53]
	v_pk_mul_f32 v[80:81], v[108:109], v[108:109]
	v_pk_fma_f32 v[52:53], v[78:79], v[76:77], v[52:53]
	v_lshlrev_b32_e32 v76, 16, v51
	v_mul_f32_e32 v0, 0xbfb8aa3b, v52
	v_exp_f32_e32 v0, v0
	v_mul_f32_e32 v70, 0xbfb8aa3b, v53
	v_exp_f32_e32 v75, v70
	v_and_b32_e32 v77, 0xffff0000, v51
	v_add_f32_e32 v0, 1.0, v0
	v_rcp_f32_e32 v74, v0
	v_add_f32_e32 v0, 1.0, v75
	v_pk_fma_f32 v[60:61], v[68:69], v[76:77], v[60:61]
	v_rcp_f32_e32 v75, v0
	v_mul_f32_e32 v0, 0xbfb8aa3b, v60
	v_exp_f32_e32 v0, v0
	v_mul_f32_e32 v51, 0xbfb8aa3b, v61
	v_exp_f32_e32 v51, v51
	v_pk_mul_f32 v[64:65], v[52:53], v[74:75]
	v_add_f32_e32 v0, 1.0, v0
	v_rcp_f32_e32 v52, v0
	v_add_f32_e32 v0, 1.0, v51
	v_lshlrev_b32_e32 v68, 16, v50
	v_and_b32_e32 v69, 0xffff0000, v50
	v_pk_mul_f32 v[50:51], v[62:63], v[132:133]
	v_pk_mul_f32 v[126:127], v[56:57], v[56:57]
	v_pk_fma_f32 v[50:51], v[58:59], v[110:111], v[50:51]
	v_pk_mul_f32 v[62:63], v[64:65], v[64:65]
	v_pk_fma_f32 v[50:51], v[66:67], v[68:69], v[50:51]
	v_mov_b32_e32 v67, v116
	v_mul_f32_e32 v53, 0xbfb8aa3b, v50
	v_exp_f32_e32 v58, v53
	v_mul_f32_e32 v53, 0xbfb8aa3b, v51
	v_exp_f32_e32 v59, v53
	v_rcp_f32_e32 v53, v0
	v_add_f32_e32 v0, 1.0, v58
	v_rcp_f32_e32 v58, v0
	v_add_f32_e32 v0, 1.0, v59
	v_rcp_f32_e32 v59, v0
	v_pk_mul_f32 v[60:61], v[60:61], v[52:53]
	v_pk_mul_f32 v[100:101], v[100:101], v[122:123]
	v_pk_mul_f32 v[52:53], v[60:61], v[60:61]
	v_pk_mul_f32 v[58:59], v[50:51], v[58:59]
	v_pk_mul_f32 v[122:123], v[100:101], v[100:101]
	v_pk_mul_f32 v[50:51], v[58:59], v[58:59]
	v_pk_mul_f32 v[70:71], v[72:73], v[72:73]
	v_mov_b32_e32 v66, v50
	v_mov_b32_e32 v116, v51
	v_pk_add_f32 v[50:51], v[66:67], v[116:117]
	v_mov_b32_e32 v66, v52
	v_mov_b32_e32 v67, v80
	v_pk_add_f32 v[50:51], v[66:67], v[50:51]
	v_mov_b32_e32 v80, v53
	v_pk_add_f32 v[50:51], v[80:81], v[50:51]
	v_mov_b32_e32 v52, v62
	v_mov_b32_e32 v53, v126
	v_pk_add_f32 v[50:51], v[52:53], v[50:51]
	v_mov_b32_e32 v126, v63
	v_pk_add_f32 v[50:51], v[126:127], v[50:51]
	v_mov_b32_e32 v52, v70
	v_mov_b32_e32 v53, v122
	v_pk_add_f32 v[50:51], v[52:53], v[50:51]
	v_mov_b32_e32 v122, v71
	v_pk_add_f32 v[50:51], v[122:123], v[50:51]
	v_cvt_pk_bf16_f32 v104, v98, v99
	v_cvt_pk_bf16_f32 v105, v94, v95
	v_mov_b32_dpp v53, v51 quad_perm:[1,0,3,2] row_mask:0xf bank_mask:0xf bound_ctrl:1
	v_mov_b32_dpp v52, v50 quad_perm:[1,0,3,2] row_mask:0xf bank_mask:0xf bound_ctrl:1
	v_pk_add_f32 v[50:51], v[50:51], v[52:53]
	v_cvt_pk_bf16_f32 v106, v90, v91
	v_cvt_pk_bf16_f32 v107, v86, v87
	v_mov_b32_dpp v53, v51 quad_perm:[2,3,0,1] row_mask:0xf bank_mask:0xf bound_ctrl:1
	v_mov_b32_dpp v52, v50 quad_perm:[2,3,0,1] row_mask:0xf bank_mask:0xf bound_ctrl:1
	v_pk_add_f32 v[50:51], v[50:51], v[52:53]
	ds_write_b128 v130, v[104:107] offset:17408
	s_nop 0
	v_mov_b32_dpp v53, v51 row_half_mirror row_mask:0xf bank_mask:0xf bound_ctrl:1
	v_mov_b32_dpp v52, v50 row_half_mirror row_mask:0xf bank_mask:0xf bound_ctrl:1
	v_pk_add_f32 v[50:51], v[50:51], v[52:53]
	s_nop 1
	v_mov_b32_dpp v53, v51 row_mirror row_mask:0xf bank_mask:0xf bound_ctrl:1
	v_mov_b32_dpp v52, v50 row_mirror row_mask:0xf bank_mask:0xf bound_ctrl:1
	v_pk_add_f32 v[50:51], v[50:51], v[52:53]
	s_nop 0
	v_pk_add_f32 v[52:53], v[50:51], s[2:3] op_sel_hi:[1,0]
	s_nop 0
	v_mul_f32_e32 v0, 0x4b800000, v53
	v_cmp_gt_f32_e32 vcc, s72, v53
	s_nop 1
	v_cndmask_b32_e32 v0, v53, v0, vcc
	v_rsq_f32_e32 v0, v0
	s_nop 0
	v_mul_f32_e32 v50, 0x45800000, v0
	v_cndmask_b32_e32 v0, v0, v50, vcc
	v_pk_mul_f32 v[54:55], v[54:55], v[0:1] op_sel_hi:[1,0]
	v_pk_mul_f32 v[62:63], v[108:109], v[0:1] op_sel_hi:[1,0]
	v_pk_mul_f32 v[56:57], v[56:57], v[0:1] op_sel_hi:[1,0]
	v_pk_mul_f32 v[66:67], v[100:101], v[0:1] op_sel_hi:[1,0]
	v_mul_f32_e32 v0, 0x4b800000, v52
	v_cmp_gt_f32_e32 vcc, s72, v52
	v_cvt_pk_bf16_f32 v50, v54, v55
	v_cvt_pk_bf16_f32 v51, v62, v63
	v_cndmask_b32_e32 v0, v52, v0, vcc
	v_rsq_f32_e32 v0, v0
	v_cvt_pk_bf16_f32 v52, v56, v57
	v_cvt_pk_bf16_f32 v53, v66, v67
	ds_write_b128 v102, v[50:53] offset:17408
	v_mul_f32_e32 v50, 0x45800000, v0
	v_cndmask_b32_e32 v0, v0, v50, vcc
	v_pk_mul_f32 v[58:59], v[58:59], v[0:1] op_sel_hi:[1,0]
	v_pk_mul_f32 v[60:61], v[60:61], v[0:1] op_sel_hi:[1,0]
	v_pk_mul_f32 v[64:65], v[64:65], v[0:1] op_sel_hi:[1,0]
	v_pk_mul_f32 v[68:69], v[72:73], v[0:1] op_sel_hi:[1,0]
	v_cvt_pk_bf16_f32 v50, v58, v59
	v_cvt_pk_bf16_f32 v51, v60, v61
	v_cvt_pk_bf16_f32 v52, v64, v65
	v_cvt_pk_bf16_f32 v53, v68, v69
	ds_write_b128 v96, v[50:53] offset:17408
	v_cndmask_b32_e64 v0, v58, v92, s[44:45]
	v_cndmask_b32_e64 v50, v54, v98, s[44:45]
	v_cndmask_b32_e64 v51, v98, v54, s[44:45]
	v_cndmask_b32_e64 v52, v92, v58, s[44:45]
	v_cvt_pk_bf16_f32 v50, v0, v50
	v_mad_u32_u24 v0, v167, s0, v169
	v_cvt_pk_bf16_f32 v51, v51, v52
	v_lshl_add_u32 v0, v0, 1, v146
	v_cndmask_b32_e64 v52, v59, v93, s[44:45]
	v_cndmask_b32_e64 v53, v55, v99, s[44:45]
	v_cndmask_b32_e64 v54, v99, v55, s[44:45]
	v_cndmask_b32_e64 v55, v93, v59, s[44:45]
	v_cvt_pk_bf16_f32 v52, v52, v53
	v_cvt_pk_bf16_f32 v53, v54, v55
	v_add_u32_e32 v70, 0x8800, v0
	ds_write2_b64 v70, v[50:51], v[52:53] offset1:18
	v_cndmask_b32_e64 v50, v60, v88, s[44:45]
	v_cndmask_b32_e64 v51, v62, v94, s[44:45]
	v_cndmask_b32_e64 v52, v94, v62, s[44:45]
	v_cndmask_b32_e64 v53, v88, v60, s[44:45]
	v_cvt_pk_bf16_f32 v50, v50, v51
	v_cvt_pk_bf16_f32 v51, v52, v53
	v_cndmask_b32_e64 v52, v61, v89, s[44:45]
	v_cndmask_b32_e64 v53, v63, v95, s[44:45]
	v_cndmask_b32_e64 v54, v95, v63, s[44:45]
	v_cndmask_b32_e64 v55, v89, v61, s[44:45]
	v_cvt_pk_bf16_f32 v52, v52, v53
	v_cvt_pk_bf16_f32 v53, v54, v55
	ds_write2_b64 v70, v[50:51], v[52:53] offset0:36 offset1:54
	v_cndmask_b32_e64 v50, v64, v84, s[44:45]
	v_cndmask_b32_e64 v51, v56, v90, s[44:45]
	v_cndmask_b32_e64 v52, v90, v56, s[44:45]
	v_cndmask_b32_e64 v53, v84, v64, s[44:45]
	v_cvt_pk_bf16_f32 v50, v50, v51
	v_cvt_pk_bf16_f32 v51, v52, v53
	v_cndmask_b32_e64 v52, v65, v85, s[44:45]
	v_cndmask_b32_e64 v53, v57, v91, s[44:45]
	v_cndmask_b32_e64 v54, v91, v57, s[44:45]
	v_cndmask_b32_e64 v55, v85, v65, s[44:45]
	v_cvt_pk_bf16_f32 v52, v52, v53
	v_cvt_pk_bf16_f32 v53, v54, v55
	v_lshlrev_b32_e32 v54, 16, v10
	v_lshlrev_b32_e32 v56, 16, v6
	v_mov_b32_e32 v57, v54
	v_lshlrev_b32_e32 v55, 16, v2
	v_mov_b32_e32 v58, v56
	s_waitcnt vmcnt(3)
	v_pk_mul_f32 v[56:57], v[42:43], v[56:57] op_sel_hi:[0,1]
	ds_write2_b64 v70, v[50:51], v[52:53] offset0:72 offset1:90
	v_cndmask_b32_e64 v50, v68, v82, s[44:45]
	v_cndmask_b32_e64 v51, v66, v86, s[44:45]
	v_cndmask_b32_e64 v52, v86, v66, s[44:45]
	v_cndmask_b32_e64 v53, v82, v68, s[44:45]
	v_lshlrev_b32_e32 v59, 16, v18
	v_pk_fma_f32 v[54:55], v[38:39], v[54:55], v[56:57] op_sel_hi:[0,1,1]
	v_cvt_pk_bf16_f32 v50, v50, v51
	v_cvt_pk_bf16_f32 v51, v52, v53
	v_cndmask_b32_e64 v52, v69, v83, s[44:45]
	v_cndmask_b32_e64 v53, v67, v87, s[44:45]
	s_waitcnt vmcnt(1)
	v_pk_fma_f32 v[54:55], v[46:47], v[58:59], v[54:55] op_sel:[0,1,0] op_sel_hi:[0,0,1]
	v_cvt_pk_bf16_f32 v52, v52, v53
	v_mul_f32_e32 v53, 0xbfb8aa3b, v55
	v_exp_f32_e32 v53, v53
	v_mul_f32_e32 v56, 0xbfb8aa3b, v54
	v_exp_f32_e32 v56, v56
	v_lshlrev_b32_e32 v61, 16, v14
	v_mov_b32_e32 v60, v59
	v_add_f32_e32 v53, 1.0, v53
	v_rcp_f32_e32 v63, v53
	v_add_f32_e32 v53, 1.0, v56
	v_mov_b32_e32 v56, v61
	v_pk_mul_f32 v[60:61], v[42:43], v[60:61] op_sel_hi:[0,1]
	v_lshlrev_b32_e32 v57, 16, v22
	v_pk_fma_f32 v[58:59], v[38:39], v[58:59], v[60:61] op_sel_hi:[0,1,1]
	v_pk_fma_f32 v[56:57], v[46:47], v[56:57], v[58:59] op_sel_hi:[0,1,1]
	v_mul_f32_e32 v58, 0xbfb8aa3b, v56
	v_exp_f32_e32 v58, v58
	v_mul_f32_e32 v59, 0xbfb8aa3b, v57
	v_exp_f32_e32 v59, v59
	v_rcp_f32_e32 v62, v53
	v_add_f32_e32 v53, 1.0, v58
	v_rcp_f32_e32 v58, v53
	v_add_f32_e32 v53, 1.0, v59
	v_rcp_f32_e32 v59, v53
	v_cndmask_b32_e64 v64, v87, v67, s[44:45]
	v_cndmask_b32_e64 v65, v83, v69, s[44:45]
	v_cvt_pk_bf16_f32 v53, v64, v65
	ds_write2_b64 v70, v[50:51], v[52:53] offset0:108 offset1:126
	v_pk_mul_f32 v[50:51], v[54:55], v[62:63]
	v_pk_mul_f32 v[52:53], v[56:57], v[58:59]
	v_and_b32_e32 v55, 0xffff0000, v18
	v_cndmask_b32_e64 v61, v52, v50, s[44:45]
	v_cndmask_b32_e64 v63, v50, v52, s[44:45]
	v_and_b32_e32 v50, 0xffff0000, v10
	v_cndmask_b32_e64 v60, v53, v51, s[44:45]
	v_cndmask_b32_e64 v62, v51, v53, s[44:45]
	v_and_b32_e32 v52, 0xffff0000, v6
	v_mov_b32_e32 v53, v50
	v_and_b32_e32 v51, 0xffff0000, v2
	v_mov_b32_e32 v54, v52
	v_pk_mul_f32 v[52:53], v[42:43], v[52:53] op_sel:[1,0]
	v_and_b32_e32 v57, 0xffff0000, v14
	v_pk_fma_f32 v[50:51], v[38:39], v[50:51], v[52:53] op_sel:[1,0,0]
	v_mov_b32_e32 v56, v55
	v_pk_fma_f32 v[50:51], v[46:47], v[54:55], v[50:51] op_sel:[1,1,0] op_sel_hi:[1,0,1]
	v_pk_mul_f32 v[42:43], v[42:43], v[56:57] op_sel:[1,0]
	v_mul_f32_e32 v2, 0xbfb8aa3b, v51
	v_exp_f32_e32 v2, v2
	v_mul_f32_e32 v6, 0xbfb8aa3b, v50
	v_exp_f32_e32 v6, v6
	v_and_b32_e32 v53, 0xffff0000, v22
	v_mov_b32_e32 v52, v57
	v_pk_fma_f32 v[38:39], v[38:39], v[54:55], v[42:43] op_sel:[1,0,0]
	v_add_f32_e32 v2, 1.0, v2
	v_pk_fma_f32 v[38:39], v[46:47], v[52:53], v[38:39] op_sel:[1,0,0]
	v_rcp_f32_e32 v59, v2
	v_add_f32_e32 v2, 1.0, v6
	v_mul_f32_e32 v6, 0xbfb8aa3b, v38
	v_exp_f32_e32 v6, v6
	v_mul_f32_e32 v10, 0xbfb8aa3b, v39
	v_exp_f32_e32 v10, v10
	v_rcp_f32_e32 v58, v2
	v_add_f32_e32 v2, 1.0, v6
	v_rcp_f32_e32 v42, v2
	v_add_f32_e32 v2, 1.0, v10
	v_rcp_f32_e32 v43, v2
	v_pk_mul_f32 v[50:51], v[50:51], v[58:59]
	v_lshlrev_b32_e32 v53, 16, v19
	v_lshlrev_b32_e32 v55, 16, v15
	v_pk_mul_f32 v[38:39], v[38:39], v[42:43]
	v_lshlrev_b32_e32 v42, 16, v11
	v_cndmask_b32_e64 v2, v39, v51, s[44:45]
	v_cndmask_b32_e64 v6, v38, v50, s[44:45]
	v_cndmask_b32_e64 v10, v51, v39, s[44:45]
	v_cndmask_b32_e64 v14, v50, v38, s[44:45]
	v_lshlrev_b32_e32 v50, 16, v7
	v_mov_b32_e32 v51, v42
	v_lshlrev_b32_e32 v43, 16, v3
	v_mov_b32_e32 v52, v50
	v_pk_mul_f32 v[50:51], v[44:45], v[50:51] op_sel_hi:[0,1]
	v_pk_fma_f32 v[42:43], v[40:41], v[42:43], v[50:51] op_sel_hi:[0,1,1]
	v_pk_fma_f32 v[42:43], v[48:49], v[52:53], v[42:43] op_sel:[0,1,0] op_sel_hi:[0,0,1]
	v_cvt_pk_bf16_f32 v38, v2, v6
	v_mul_f32_e32 v2, 0xbfb8aa3b, v43
	v_exp_f32_e32 v2, v2
	v_mul_f32_e32 v6, 0xbfb8aa3b, v42
	v_exp_f32_e32 v6, v6
	v_mov_b32_e32 v54, v53
	v_mov_b32_e32 v50, v55
	v_pk_mul_f32 v[54:55], v[44:45], v[54:55] op_sel_hi:[0,1]
	v_lshlrev_b32_e32 v51, 16, v23
	v_pk_fma_f32 v[52:53], v[40:41], v[52:53], v[54:55] op_sel_hi:[0,1,1]
	v_add_f32_e32 v2, 1.0, v2
	v_pk_fma_f32 v[50:51], v[48:49], v[50:51], v[52:53] op_sel_hi:[0,1,1]
	v_rcp_f32_e32 v57, v2
	v_add_f32_e32 v2, 1.0, v6
	v_mul_f32_e32 v6, 0xbfb8aa3b, v50
	v_cvt_pk_bf16_f32 v39, v14, v10
	v_exp_f32_e32 v6, v6
	v_mul_f32_e32 v10, 0xbfb8aa3b, v51
	v_exp_f32_e32 v10, v10
	v_rcp_f32_e32 v56, v2
	v_add_f32_e32 v2, 1.0, v6
	v_rcp_f32_e32 v52, v2
	v_add_f32_e32 v2, 1.0, v10
	v_rcp_f32_e32 v53, v2
	v_and_b32_e32 v2, 0xffff0000, v11
	v_and_b32_e32 v6, 0xffff0000, v7
	v_mov_b32_e32 v7, v2
	v_mov_b32_e32 v18, v45
	v_add_u32_e32 v40, 0xd000, v0
	v_and_b32_e32 v3, 0xffff0000, v3
	v_mov_b32_e32 v10, v6
	v_mov_b32_e32 v0, v41
	v_pk_mul_f32 v[6:7], v[18:19], v[6:7] op_sel_hi:[0,1]
	v_and_b32_e32 v11, 0xffff0000, v19
	v_pk_fma_f32 v[2:3], v[0:1], v[2:3], v[6:7] op_sel_hi:[0,1,1]
	v_mov_b32_e32 v22, v49
	v_pk_fma_f32 v[2:3], v[22:23], v[10:11], v[2:3] op_sel:[0,1,0] op_sel_hi:[0,0,1]
	v_mul_f32_e32 v6, 0xbfb8aa3b, v3
	v_exp_f32_e32 v19, v6
	v_mul_f32_e32 v6, 0xbfb8aa3b, v2
	v_and_b32_e32 v7, 0xffff0000, v23
	v_exp_f32_e32 v23, v6
	v_add_f32_e32 v19, 1.0, v19
	v_rcp_f32_e32 v19, v19
	v_and_b32_e32 v15, 0xffff0000, v15
	v_mov_b32_e32 v14, v11
	v_mov_b32_e32 v6, v15
	v_pk_mul_f32 v[14:15], v[18:19], v[14:15] op_sel_hi:[0,1]
	v_add_f32_e32 v23, 1.0, v23
	v_pk_fma_f32 v[10:11], v[0:1], v[10:11], v[14:15] op_sel_hi:[0,1,1]
	v_pk_fma_f32 v[6:7], v[22:23], v[6:7], v[10:11] op_sel_hi:[0,1,1]
	v_mul_f32_e32 v0, 0xbfb8aa3b, v6
	v_exp_f32_e32 v0, v0
	v_mul_f32_e32 v10, 0xbfb8aa3b, v7
	v_exp_f32_e32 v11, v10
	v_rcp_f32_e32 v18, v23
	v_add_f32_e32 v0, 1.0, v0
	v_rcp_f32_e32 v10, v0
	v_add_f32_e32 v0, 1.0, v11
	v_rcp_f32_e32 v11, v0
	v_pk_mul_f32 v[2:3], v[2:3], v[18:19]
	v_lshlrev_b32_e32 v19, 16, v20
	v_cvt_pk_bf16_f32 v46, v60, v61
	v_pk_mul_f32 v[6:7], v[6:7], v[10:11]
	v_cvt_pk_bf16_f32 v47, v63, v62
	v_cndmask_b32_e64 v0, v7, v3, s[44:45]
	v_cndmask_b32_e64 v10, v6, v2, s[44:45]
	v_cndmask_b32_e64 v41, v2, v6, s[44:45]
	v_lshlrev_b32_e32 v6, 16, v12
	v_cvt_pk_bf16_f32 v2, v0, v10
	v_lshlrev_b32_e32 v10, 16, v8
	v_mov_b32_e32 v11, v6
	v_cndmask_b32_e64 v3, v3, v7, s[44:45]
	v_lshlrev_b32_e32 v7, 16, v4
	v_mov_b32_e32 v18, v10
	v_pk_mul_f32 v[10:11], v[30:31], v[10:11] op_sel_hi:[0,1]
	v_pk_fma_f32 v[6:7], v[26:27], v[6:7], v[10:11] op_sel_hi:[0,1,1]
	s_waitcnt vmcnt(0)
	v_pk_fma_f32 v[6:7], v[34:35], v[18:19], v[6:7] op_sel:[0,1,0] op_sel_hi:[0,0,1]
	v_mul_f32_e32 v0, 0xbfb8aa3b, v7
	v_exp_f32_e32 v0, v0
	v_mul_f32_e32 v10, 0xbfb8aa3b, v6
	v_exp_f32_e32 v10, v10
	ds_write2_b64 v40, v[46:47], v[38:39] offset1:18
	v_pk_mul_f32 v[38:39], v[42:43], v[56:57]
	v_pk_mul_f32 v[42:43], v[50:51], v[52:53]
	v_lshlrev_b32_e32 v23, 16, v16
	v_cndmask_b32_e64 v44, v43, v39, s[44:45]
	v_cndmask_b32_e64 v46, v42, v38, s[44:45]
	v_cndmask_b32_e64 v39, v39, v43, s[44:45]
	v_cndmask_b32_e64 v38, v38, v42, s[44:45]
	v_mov_b32_e32 v22, v19
	v_add_f32_e32 v0, 1.0, v0
	v_cvt_pk_bf16_f32 v15, v38, v39
	v_rcp_f32_e32 v39, v0
	v_add_f32_e32 v0, 1.0, v10
	v_mov_b32_e32 v10, v23
	v_pk_mul_f32 v[22:23], v[30:31], v[22:23] op_sel_hi:[0,1]
	v_lshlrev_b32_e32 v11, 16, v24
	v_pk_fma_f32 v[18:19], v[26:27], v[18:19], v[22:23] op_sel_hi:[0,1,1]
	v_pk_fma_f32 v[10:11], v[34:35], v[10:11], v[18:19] op_sel_hi:[0,1,1]
	v_mul_f32_e32 v18, 0xbfb8aa3b, v10
	v_exp_f32_e32 v18, v18
	v_mul_f32_e32 v19, 0xbfb8aa3b, v11
	v_exp_f32_e32 v19, v19
	v_rcp_f32_e32 v38, v0
	v_add_f32_e32 v0, 1.0, v18
	v_rcp_f32_e32 v18, v0
	v_add_f32_e32 v0, 1.0, v19
	v_rcp_f32_e32 v19, v0
	v_cvt_pk_bf16_f32 v14, v44, v46
	v_cvt_pk_bf16_f32 v3, v41, v3
	ds_write2_b64 v40, v[14:15], v[2:3] offset0:36 offset1:54
	v_pk_mul_f32 v[2:3], v[6:7], v[38:39]
	v_pk_mul_f32 v[6:7], v[10:11], v[18:19]
	v_and_b32_e32 v11, 0xffff0000, v20
	v_cndmask_b32_e64 v22, v6, v2, s[44:45]
	v_cndmask_b32_e64 v38, v2, v6, s[44:45]
	v_and_b32_e32 v2, 0xffff0000, v12
	v_cndmask_b32_e64 v0, v7, v3, s[44:45]
	v_cndmask_b32_e64 v23, v3, v7, s[44:45]
	v_and_b32_e32 v6, 0xffff0000, v8
	v_mov_b32_e32 v7, v2
	v_and_b32_e32 v3, 0xffff0000, v4
	v_mov_b32_e32 v10, v6
	v_pk_mul_f32 v[6:7], v[30:31], v[6:7] op_sel:[1,0]
	v_and_b32_e32 v15, 0xffff0000, v16
	v_pk_fma_f32 v[2:3], v[26:27], v[2:3], v[6:7] op_sel:[1,0,0]
	v_mov_b32_e32 v14, v11
	v_pk_fma_f32 v[2:3], v[34:35], v[10:11], v[2:3] op_sel:[1,1,0] op_sel_hi:[1,0,1]
	v_and_b32_e32 v7, 0xffff0000, v24
	v_mul_f32_e32 v4, 0xbfb8aa3b, v3
	v_exp_f32_e32 v4, v4
	v_mul_f32_e32 v6, 0xbfb8aa3b, v2
	v_exp_f32_e32 v8, v6
	v_mov_b32_e32 v6, v15
	v_pk_mul_f32 v[14:15], v[30:31], v[14:15] op_sel:[1,0]
	v_add_f32_e32 v4, 1.0, v4
	v_pk_fma_f32 v[10:11], v[26:27], v[10:11], v[14:15] op_sel:[1,0,0]
	v_rcp_f32_e32 v19, v4
	v_pk_fma_f32 v[6:7], v[34:35], v[6:7], v[10:11] op_sel:[1,0,0]
	v_add_f32_e32 v4, 1.0, v8
	v_mul_f32_e32 v8, 0xbfb8aa3b, v6
	v_exp_f32_e32 v8, v8
	v_mul_f32_e32 v10, 0xbfb8aa3b, v7
	v_exp_f32_e32 v11, v10
	v_rcp_f32_e32 v18, v4
	v_add_f32_e32 v4, 1.0, v8
	v_rcp_f32_e32 v10, v4
	v_add_f32_e32 v4, 1.0, v11
	v_rcp_f32_e32 v11, v4
	v_pk_mul_f32 v[2:3], v[2:3], v[18:19]
	v_cvt_pk_bf16_f32 v14, v0, v22
	v_lshlrev_b32_e32 v19, 16, v21
	v_pk_mul_f32 v[6:7], v[6:7], v[10:11]
	v_lshlrev_b32_e32 v10, 16, v9
	v_cndmask_b32_e64 v4, v6, v2, s[44:45]
	v_cndmask_b32_e64 v8, v2, v6, s[44:45]
	v_lshlrev_b32_e32 v6, 16, v13
	v_mov_b32_e32 v11, v6
	v_cndmask_b32_e64 v0, v7, v3, s[44:45]
	v_cndmask_b32_e64 v3, v3, v7, s[44:45]
	v_lshlrev_b32_e32 v7, 16, v5
	v_mov_b32_e32 v18, v10
	v_pk_mul_f32 v[10:11], v[32:33], v[10:11] op_sel_hi:[0,1]
	v_pk_fma_f32 v[6:7], v[28:29], v[6:7], v[10:11] op_sel_hi:[0,1,1]
	v_pk_fma_f32 v[6:7], v[36:37], v[18:19], v[6:7] op_sel:[0,1,0] op_sel_hi:[0,0,1]
	v_cvt_pk_bf16_f32 v2, v0, v4
	v_mul_f32_e32 v0, 0xbfb8aa3b, v7
	v_exp_f32_e32 v0, v0
	v_mul_f32_e32 v4, 0xbfb8aa3b, v6
	v_cvt_pk_bf16_f32 v15, v38, v23
	v_lshlrev_b32_e32 v23, 16, v17
	v_exp_f32_e32 v4, v4
	v_mov_b32_e32 v22, v19
	v_mov_b32_e32 v10, v23
	v_pk_mul_f32 v[22:23], v[32:33], v[22:23] op_sel_hi:[0,1]
	v_lshlrev_b32_e32 v11, 16, v25
	v_pk_fma_f32 v[18:19], v[28:29], v[18:19], v[22:23] op_sel_hi:[0,1,1]
	v_add_f32_e32 v0, 1.0, v0
	v_pk_fma_f32 v[10:11], v[36:37], v[10:11], v[18:19] op_sel_hi:[0,1,1]
	v_rcp_f32_e32 v27, v0
	v_add_f32_e32 v0, 1.0, v4
	v_mul_f32_e32 v4, 0xbfb8aa3b, v10
	v_exp_f32_e32 v4, v4
	v_mul_f32_e32 v12, 0xbfb8aa3b, v11
	v_exp_f32_e32 v12, v12
	v_rcp_f32_e32 v26, v0
	v_add_f32_e32 v0, 1.0, v4
	v_rcp_f32_e32 v18, v0
	v_add_f32_e32 v0, 1.0, v12
	v_rcp_f32_e32 v19, v0
	v_cvt_pk_bf16_f32 v3, v8, v3
	ds_write2_b64 v40, v[14:15], v[2:3] offset0:72 offset1:90
	v_pk_mul_f32 v[2:3], v[6:7], v[26:27]
	v_pk_mul_f32 v[6:7], v[10:11], v[18:19]
	v_and_b32_e32 v4, 0xffff0000, v9
	v_cndmask_b32_e64 v15, v6, v2, s[44:45]
	v_cndmask_b32_e64 v18, v2, v6, s[44:45]
	v_and_b32_e32 v2, 0xffff0000, v13
	v_cndmask_b32_e64 v14, v7, v3, s[44:45]
	v_cndmask_b32_e64 v16, v3, v7, s[44:45]
	v_and_b32_e32 v3, 0xffff0000, v5
	v_mov_b32_e32 v5, v2
	v_mov_b32_e32 v10, v33
	v_mov_b32_e32 v6, v4
	v_mov_b32_e32 v0, v29
	v_pk_mul_f32 v[4:5], v[10:11], v[4:5] op_sel_hi:[0,1]
	v_and_b32_e32 v7, 0xffff0000, v21
	v_pk_fma_f32 v[2:3], v[0:1], v[2:3], v[4:5] op_sel_hi:[0,1,1]
	v_mov_b32_e32 v12, v37
	v_pk_fma_f32 v[2:3], v[12:13], v[6:7], v[2:3] op_sel:[0,1,0] op_sel_hi:[0,0,1]
	v_mul_f32_e32 v4, 0xbfb8aa3b, v3
	v_exp_f32_e32 v11, v4
	v_mul_f32_e32 v4, 0xbfb8aa3b, v2
	v_exp_f32_e32 v13, v4
	v_and_b32_e32 v9, 0xffff0000, v17
	v_add_f32_e32 v11, 1.0, v11
	v_rcp_f32_e32 v11, v11
	v_mov_b32_e32 v8, v7
	v_mov_b32_e32 v4, v9
	v_and_b32_e32 v5, 0xffff0000, v25
	v_pk_mul_f32 v[8:9], v[10:11], v[8:9] op_sel_hi:[0,1]
	v_add_f32_e32 v13, 1.0, v13
	v_pk_fma_f32 v[6:7], v[0:1], v[6:7], v[8:9] op_sel_hi:[0,1,1]
	v_pk_fma_f32 v[4:5], v[12:13], v[4:5], v[6:7] op_sel_hi:[0,1,1]
	v_mul_f32_e32 v0, 0xbfb8aa3b, v4
	v_exp_f32_e32 v0, v0
	v_mul_f32_e32 v6, 0xbfb8aa3b, v5
	v_exp_f32_e32 v7, v6
	v_rcp_f32_e32 v10, v13
	v_add_f32_e32 v0, 1.0, v0
	v_rcp_f32_e32 v6, v0
	v_add_f32_e32 v0, 1.0, v7
	v_rcp_f32_e32 v7, v0
	v_pk_mul_f32 v[2:3], v[2:3], v[10:11]
	v_cvt_pk_bf16_f32 v8, v14, v15
	v_cvt_pk_bf16_f32 v9, v18, v16
	v_pk_mul_f32 v[4:5], v[4:5], v[6:7]
	s_nop 0
	v_cndmask_b32_e64 v0, v5, v3, s[44:45]
	v_cndmask_b32_e64 v6, v4, v2, s[44:45]
	v_cndmask_b32_e64 v3, v3, v5, s[44:45]
	v_cndmask_b32_e64 v4, v2, v4, s[44:45]
	v_cvt_pk_bf16_f32 v2, v0, v6
	v_cvt_pk_bf16_f32 v3, v4, v3
	ds_write2_b64 v40, v[8:9], v[2:3] offset0:108 offset1:126
	s_waitcnt lgkmcnt(0)
	v_readlane_b32 s0, v255, 26
	s_nop 3
	s_cmp_eq_u32 s0, 0
	s_cbranch_scc1 .Lsb_nopend
	v_readlane_b32 s22, v251, 13
	v_readlane_b32 s23, v251, 14
	s_mov_b32 s1, 0
	v_mov_b32_e32 v2, 0
	s_nop 3
